# GEMM1 unit header: division by the (always 4) group height replaced by shift/mask (no v_rcp/readfirstlane round trip)
# speedup vs baseline: 1.0090x; 1.0036x over previous
.LBB0_286:
	s_add_i32 s77, s77, 1
	v_readlane_b32 s40, v253, 35
	v_readlane_b32 s43, v252, 7
	s_mul_i32 s40, s77, s40
	s_mul_hi_u32 s41, s77, s43
	s_add_i32 s41, s41, s40
	s_mul_i32 s40, s77, s43
	s_add_u32 s54, s40, s95
	v_readlane_b32 s40, v253, 27
	s_addc_u32 s55, s41, s40
	v_mov_b64_e32 v[0:1], 0x288
	v_cmp_lt_i64_e64 s[40:41], s[54:55], v[0:1]
	v_mov_b64_e32 v[0:1], 0x287
	v_cmp_gt_i64_e32 vcc, s[54:55], v[0:1]
	s_cbranch_vccnz .LBB0_288
	s_ashr_i32 s42, s54, 31
	s_lshr_b32 s42, s42, 29
	s_add_i32 s42, s54, s42
	s_ashr_i32 s43, s42, 3
	s_and_b32 s42, s42, -8
	s_sub_i32 s42, s54, s42
	s_cmp_lt_i32 s42, 0
	s_movk_i32 s52, 0x52
	s_cselect_b32 s52, s52, 0x51
	s_mul_i32 s42, s52, s42
	s_add_i32 s42, s42, s43
	s_mul_hi_i32 s43, s42, 0x38e38e39
	s_lshr_b32 s52, s43, 31
	s_ashr_i32 s43, s43, 3
	s_add_i32 s43, s43, s52
	s_lshl_b32 s52, s43, 2
	s_mul_i32 s43, s43, 36
	s_sub_i32 s43, s42, s43
	s_lshr_b32 s42, s43, 2
	s_and_b32 s43, s43, 3
	s_add_i32 s52, s43, s52
